# v43 + EpiUp: bj=1 halo loads issued with the bj=0 ones at the epilogue top (one exposed miss latency instead of two)
# speedup vs baseline: 1.0093x; 1.0027x over previous
;     __device__ __forceinline__ void operator()(Acc& acc, const Unit& u, int wr, int wc, int fr, int fq, LAS unsigned char* lds, int tid) const {
;     ...
;         for (int bj = 0; bj < 2; ++bj) {
;             const unsigned colp = u.pn * 256 + bj * 128 + wc * 32 + 8 * fq;
;             const unsigned coll = bj * FF + u.pn * 128 + wc * 32 + 8 * fq;
; #pragma unroll
;             for (int n = 0; n < 2; ++n) {
;                 f32x4 c0 = ldf4(cw, coll + 4u * n), c1 = ldf4(cw, (unsigned)FF2 + coll + 4u * n), c2 = ldf4(cw, 2u * FF2 + coll + 4u * n);
;                 if constexpr (I8) { const f32x4 swv = ldf4(sw, colp + 4u * n); c0 = c0 * swv; c1 = c1 * swv; c2 = c2 * swv; }
;                 f32x4 hl = {0.f, 0.f, 0.f, 0.f}, hr = {0.f, 0.f, 0.f, 0.f};
;                 if (fr == 0 && lvalid) hl = ldf4(HALO, (2u * bk) * (unsigned)FF2 + colp + 4u * n);
;                 if (fr == 15 && rvalid) hr = ldf4(HALO, (2u * bk + 1u) * (unsigned)FF2 + colp + 4u * n);
.LBB0_1072:
	s_or_b64 exec, exec, s[60:61]
	v_or_b32_e32 v238, 0x80, v177
	v_add_u32_e32 v182, s1, v238
	v_add_u32_e32 v183, s0, v238
	v_lshlrev_b32_e32 v182, 2, v182
	v_lshlrev_b32_e32 v183, 2, v183
	s_cmp_lg_u64 s[44:45], 0
	s_cbranch_scc1 .Lzs_4e
	v_mov_b32_e32 v184, 0
	v_mov_b32_e32 v185, 0
	v_mov_b32_e32 v186, 0
	v_mov_b32_e32 v187, 0
.Lzs_4e:
	s_and_saveexec_b64 s[60:61], s[44:45]
	global_load_dwordx4 v[184:187], v182, s[38:39]
	s_or_b64 exec, exec, s[60:61]
	s_cbranch_vccnz .Lzs_5e
	v_mov_b32_e32 v204, 0
	v_mov_b32_e32 v205, 0
	v_mov_b32_e32 v206, 0
	v_mov_b32_e32 v207, 0
.Lzs_5e:
	s_and_saveexec_b64 s[60:61], vcc
	global_load_dwordx4 v[204:207], v183, s[38:39]
	s_or_b64 exec, exec, s[60:61]
	v_mov_b32_e32 v147, v209
	v_lshl_add_u64 v[180:181], s[28:29], 0, v[146:147]
	v_cvt_f32_i32_e32 v147, v161
	v_cvt_f32_i32_e32 v146, v160
	v_cvt_f32_i32_e32 v161, v163
	v_cvt_f32_i32_e32 v160, v162
	v_lshl_add_u64 v[164:165], s[22:23], 0, v[208:209]
	v_cvt_f32_i32_e32 v149, v149
	v_cvt_f32_i32_e32 v148, v148
	v_cvt_f32_i32_e32 v153, v153
	v_cvt_f32_i32_e32 v152, v152
	v_cvt_f32_i32_e32 v155, v155
	v_cvt_f32_i32_e32 v154, v154
	v_cvt_f32_i32_e32 v151, v151
	v_cvt_f32_i32_e32 v150, v150
	v_cvt_f32_i32_e32 v117, v117
	v_cvt_f32_i32_e32 v116, v116
	v_cvt_f32_i32_e32 v109, v109
	v_cvt_f32_i32_e32 v108, v108
	v_cvt_f32_i32_e32 v119, v119
	v_cvt_f32_i32_e32 v118, v118
	v_cvt_f32_i32_e32 v111, v111
	v_cvt_f32_i32_e32 v110, v110
	v_cvt_f32_i32_e32 v53, v53
	v_cvt_f32_i32_e32 v52, v52
	v_cvt_f32_i32_e32 v49, v49
	v_cvt_f32_i32_e32 v48, v48
	v_cvt_f32_i32_e32 v45, v45
	v_cvt_f32_i32_e32 v44, v44
	v_cvt_f32_i32_e32 v41, v41
	v_cvt_f32_i32_e32 v40, v40
	v_cvt_f32_i32_e32 v37, v37
	v_cvt_f32_i32_e32 v36, v36
	v_cvt_f32_i32_e32 v33, v33
	v_cvt_f32_i32_e32 v32, v32
	v_cvt_f32_i32_e32 v55, v55
	v_cvt_f32_i32_e32 v54, v54
	v_cvt_f32_i32_e32 v51, v51
	v_cvt_f32_i32_e32 v50, v50
	v_cvt_f32_i32_e32 v47, v47
	v_cvt_f32_i32_e32 v46, v46
	v_cvt_f32_i32_e32 v43, v43
	v_cvt_f32_i32_e32 v42, v42
	v_cvt_f32_i32_e32 v39, v39
	v_cvt_f32_i32_e32 v38, v38
	v_cvt_f32_i32_e32 v27, v27
	v_cvt_f32_i32_e32 v26, v26
	v_cvt_f32_i32_e32 v13, v13
	v_cvt_f32_i32_e32 v12, v12
	v_cvt_f32_i32_e32 v35, v35
	v_cvt_f32_i32_e32 v34, v34
	v_cvt_f32_i32_e32 v101, v101
	v_cvt_f32_i32_e32 v100, v100
	v_cvt_f32_i32_e32 v97, v97
	v_cvt_f32_i32_e32 v96, v96
	v_cvt_f32_i32_e32 v93, v93
	v_cvt_f32_i32_e32 v92, v92
	v_cvt_f32_i32_e32 v11, v11
	v_cvt_f32_i32_e32 v10, v10
	v_cvt_f32_i32_e32 v89, v89
	v_cvt_f32_i32_e32 v88, v88
	v_cvt_f32_i32_e32 v31, v31
	v_cvt_f32_i32_e32 v30, v30
	v_cvt_f32_i32_e32 v17, v17
	v_cvt_f32_i32_e32 v16, v16
	v_cvt_f32_i32_e32 v85, v85
	v_cvt_f32_i32_e32 v84, v84
	v_cvt_f32_i32_e32 v77, v77
	v_cvt_f32_i32_e32 v79, v79
	v_cvt_f32_i32_e32 v78, v78
	v_cvt_f32_i32_e32 v76, v76
	v_cvt_f32_i32_e32 v57, v57
	v_cvt_f32_i32_e32 v59, v59
	v_cvt_f32_i32_e32 v58, v58
	v_cvt_f32_i32_e32 v56, v56
	v_cvt_f32_i32_e32 v7, v7
	v_cvt_f32_i32_e32 v6, v6
	v_cvt_f32_i32_e32 v103, v103
	v_cvt_f32_i32_e32 v102, v102
	v_cvt_f32_i32_e32 v99, v99
	v_cvt_f32_i32_e32 v98, v98
	v_cvt_f32_i32_e32 v95, v95
	v_cvt_f32_i32_e32 v94, v94
	v_cvt_f32_i32_e32 v91, v91
	v_cvt_f32_i32_e32 v90, v90
	v_cvt_f32_i32_e32 v87, v87
	v_cvt_f32_i32_e32 v86, v86
	v_cvt_f32_i32_e32 v81, v81
	v_cvt_f32_i32_e32 v80, v80
	v_cvt_f32_i32_e32 v73, v73
	v_cvt_f32_i32_e32 v72, v72
	v_cvt_f32_i32_e32 v69, v69
	v_cvt_f32_i32_e32 v68, v68
	v_cvt_f32_i32_e32 v65, v65
	v_cvt_f32_i32_e32 v64, v64
	v_cvt_f32_i32_e32 v61, v61
	v_cvt_f32_i32_e32 v60, v60
	v_cvt_f32_i32_e32 v83, v83
	v_cvt_f32_i32_e32 v82, v82
	v_cvt_f32_i32_e32 v67, v67
	v_cvt_f32_i32_e32 v66, v66
	v_cvt_f32_i32_e32 v63, v63
	v_cvt_f32_i32_e32 v62, v62
	v_cvt_f32_i32_e32 v29, v29
	v_cvt_f32_i32_e32 v28, v28
	v_cvt_f32_i32_e32 v25, v25
	v_cvt_f32_i32_e32 v24, v24
	v_cvt_f32_i32_e32 v19, v19
	v_cvt_f32_i32_e32 v18, v18
	v_cvt_f32_i32_e32 v15, v15
	v_cvt_f32_i32_e32 v14, v14
	v_cvt_f32_i32_e32 v75, v75
	v_cvt_f32_i32_e32 v74, v74
	v_cvt_f32_i32_e32 v23, v23
	v_cvt_f32_i32_e32 v22, v22
	v_cvt_f32_i32_e32 v21, v21
	v_cvt_f32_i32_e32 v20, v20
	v_cvt_f32_i32_e32 v71, v71
	v_cvt_f32_i32_e32 v70, v70
	s_waitcnt vmcnt(7)
	v_pk_mul_f32 v[224:225], v[112:113], v[146:147] op_sel_hi:[0,1]
	v_cvt_f32_i32_e32 v147, v157
	v_cvt_f32_i32_e32 v146, v156
	v_cvt_f32_i32_e32 v157, v159
	v_cvt_f32_i32_e32 v156, v158
	s_waitcnt vmcnt(6)
	v_mov_b32_e32 v158, v107
	v_add_u32_e32 v145, 0xb010, v208
	v_pk_mul_f32 v[220:221], v[112:113], v[160:161] op_sel_hi:[0,1]
	v_pk_mul_f32 v[218:219], v[158:159], v[156:157] op_sel_hi:[0,1]
	v_pk_mul_f32 v[222:223], v[158:159], v[146:147] op_sel_hi:[0,1]
	global_load_dwordx4 v[160:163], v[164:165], off offset:16
	global_load_dwordx4 v[156:159], v145, s[22:23]
	v_add_u32_e32 v145, 0x16010, v208
	global_load_dwordx4 v[164:167], v145, s[22:23]
	global_load_dwordx4 v[168:171], v[180:181], off offset:16
	s_waitcnt vmcnt(6)
	v_mov_b32_dpp v120, v222 row_shr:1 row_mask:0xf bank_mask:0xf
	v_mov_b32_dpp v124, v224 row_shl:1 row_mask:0xf bank_mask:0xf
	v_mov_b32_dpp v121, v223 row_shr:1 row_mask:0xf bank_mask:0xf
	v_mov_b32_dpp v125, v225 row_shl:1 row_mask:0xf bank_mask:0xf
	v_mov_b32_dpp v122, v218 row_shr:1 row_mask:0xf bank_mask:0xf
	v_mov_b32_dpp v126, v220 row_shl:1 row_mask:0xf bank_mask:0xf
	v_mov_b32_dpp v123, v219 row_shr:1 row_mask:0xf bank_mask:0xf
	v_mov_b32_dpp v127, v221 row_shl:1 row_mask:0xf bank_mask:0xf
	s_cmp_lg_u64 s[44:45], 0
	s_cbranch_scc1 .Lzs_2
	v_mov_b32_e32 v145, 0
	v_mov_b32_e32 v146, 0
	v_mov_b32_e32 v147, 0

;     __device__ __forceinline__ void operator()(Acc& acc, const Unit& u, int wr, int wc, int fr, int fq, LAS unsigned char* lds, int tid) const {
;     ...
;                 if (fr == 0 && lvalid) hl = ldf4(HALO, (2u * bk) * (unsigned)FF2 + colp + 4u * n);
;                 if (fr == 15 && rvalid) hr = ldf4(HALO, (2u * bk + 1u) * (unsigned)FF2 + colp + 4u * n);
.LBB0_1074:
	s_or_b64 exec, exec, s[60:61]
	s_cbranch_vccnz .Lzs_3
	v_mov_b32_e32 v172, 0
	v_mov_b32_e32 v173, 0
	v_mov_b32_e32 v174, 0
	v_mov_b32_e32 v175, 0

;     __device__ bool next(int i, Unit& u) const { return S.next(i, u); }
;     __device__ bool next(int i, Unit& u) const { const int L = i * G + c; if (L >= 3 * 44) return false; u.pm = L % 3; u.pn = L / 3; u.g = 0; u.part = 0; u.keep = 0; return true; }
;     __device__ __forceinline__ void operator()(Acc& acc, const Unit& u, int wr, int wc, int fr, int fq, LAS unsigned char* lds, int tid) const {
;     ...
;         for (int bj = 0; bj < 2; ++bj) {
;             const unsigned colp = u.pn * 256 + bj * 128 + wc * 32 + 8 * fq;
;             const unsigned coll = bj * FF + u.pn * 128 + wc * 32 + 8 * fq;
; #pragma unroll
;             for (int n = 0; n < 2; ++n) {
;                 f32x4 c0 = ldf4(cw, coll + 4u * n), c1 = ldf4(cw, (unsigned)FF2 + coll + 4u * n), c2 = ldf4(cw, 2u * FF2 + coll + 4u * n);
;                 if constexpr (I8) { const f32x4 swv = ldf4(sw, colp + 4u * n); c0 = c0 * swv; c1 = c1 * swv; c2 = c2 * swv; }
;                 f32x4 hl = {0.f, 0.f, 0.f, 0.f}, hr = {0.f, 0.f, 0.f, 0.f};
;                 if (fr == 0 && lvalid) hl = ldf4(HALO, (2u * bk) * (unsigned)FF2 + colp + 4u * n);
;                 if (fr == 15 && rvalid) hr = ldf4(HALO, (2u * bk + 1u) * (unsigned)FF2 + colp + 4u * n);
; #pragma unroll
;                 for (int e = 0; e < 4; ++e) {
;                     const float prev = dpp_shr1(hl[e], acc[1][bj][3][n][e]);
;                     const float next = dpp_shl1(hr[e], acc[0][bj][0][n][e]);
.LBB0_1076:
	s_or_b64 exec, exec, s[60:61]
	v_mov_b32_e32 v226, v107
	v_mov_b32_e32 v227, v107
	v_pk_mul_f32 v[234:235], v[226:227], v[148:149]
	v_add_u32_e32 v149, 0x5800, v208
	global_load_dwordx4 v[188:191], v149, s[22:23]
	v_add_u32_e32 v149, 0x10800, v208
	v_or_b32_e32 v148, 0x80, v177
	global_load_dwordx4 v[196:199], v149, s[22:23]
	v_add_u32_e32 v149, 0x1b800, v208
	global_load_dwordx4 v[192:195], v149, s[22:23]
	v_lshlrev_b32_e32 v149, 2, v148
	global_load_dwordx4 v[200:203], v149, s[28:29]
	v_mov_b32_e32 v228, v112
	v_mov_b32_e32 v229, v112
	v_mov_b32_e32 v178, v112
	v_mov_b32_e32 v179, v112
	v_pk_mul_f32 v[236:237], v[228:229], v[152:153]
	v_mov_b32_e32 v152, v107
	v_mov_b32_e32 v153, v107
	v_pk_mul_f32 v[232:233], v[178:179], v[154:155]
	v_pk_mul_f32 v[230:231], v[152:153], v[150:151]
	s_waitcnt vmcnt(4)
	v_mov_b32_dpp v144, v234 row_shr:1 row_mask:0xf bank_mask:0xf
	v_mov_b32_dpp v172, v236 row_shl:1 row_mask:0xf bank_mask:0xf
	v_mov_b32_dpp v145, v235 row_shr:1 row_mask:0xf bank_mask:0xf
	v_mov_b32_dpp v173, v237 row_shl:1 row_mask:0xf bank_mask:0xf
	v_mov_b32_dpp v146, v230 row_shr:1 row_mask:0xf bank_mask:0xf
	v_mov_b32_dpp v174, v232 row_shl:1 row_mask:0xf bank_mask:0xf
	v_mov_b32_dpp v147, v231 row_shr:1 row_mask:0xf bank_mask:0xf
	v_mov_b32_dpp v175, v233 row_shl:1 row_mask:0xf bank_mask:0xf
	v_add_u32_e32 v215, s1, v148
	v_add_u32_e32 v216, s0, v148
	v_mov_b32_e32 v148, 0
	v_mov_b32_e32 v150, v112
	v_mov_b32_e32 v151, v112
	v_pk_mul_f32 v[244:245], v[228:229], v[116:117]
	v_mov_b32_e32 v116, v107
	v_mov_b32_e32 v117, v107
	v_pk_mul_f32 v[242:243], v[226:227], v[108:109]
	v_add_u32_e32 v108, 0x5810, v208
	v_pk_mul_f32 v[240:241], v[150:151], v[118:119]
	v_pk_mul_f32 v[238:239], v[116:117], v[110:111]
	s_waitcnt vmcnt(9)
	v_mov_b32_e32 v176, v184
	v_mov_b32_e32 v177, v185
	v_mov_b32_e32 v178, v186
	v_mov_b32_e32 v179, v187
	global_load_dwordx4 v[116:119], v108, s[22:23]
	v_add_u32_e32 v108, 0x10810, v208
	global_load_dwordx4 v[184:187], v108, s[22:23]
	v_add_u32_e32 v108, 0x1b810, v208
	global_load_dwordx4 v[152:155], v108, s[22:23]
	s_nop 0
	global_load_dwordx4 v[180:183], v[180:181], off offset:528
	s_waitcnt vmcnt(4)
	v_mov_b32_dpp v176, v242 row_shr:1 row_mask:0xf bank_mask:0xf
	v_mov_b32_dpp v204, v244 row_shl:1 row_mask:0xf bank_mask:0xf
	v_mov_b32_dpp v177, v243 row_shr:1 row_mask:0xf bank_mask:0xf
	v_mov_b32_dpp v205, v245 row_shl:1 row_mask:0xf bank_mask:0xf
	v_mov_b32_dpp v178, v238 row_shr:1 row_mask:0xf bank_mask:0xf
	v_mov_b32_dpp v206, v240 row_shl:1 row_mask:0xf bank_mask:0xf
	v_mov_b32_dpp v179, v239 row_shr:1 row_mask:0xf bank_mask:0xf
	v_mov_b32_dpp v207, v241 row_shl:1 row_mask:0xf bank_mask:0xf
	s_cmp_lg_u64 s[44:45], 0
	s_cbranch_scc1 .Lzs_6
	v_mov_b32_e32 v149, 0
	v_mov_b32_e32 v150, 0
	v_mov_b32_e32 v151, 0
